# SB loop: QK MFMAs read K straight from the load registers v[108:123]; 8 v_mov_b64 K copies per iteration removed; vmcnt(0) on early-exit path
# speedup vs baseline: 1.0004x; 1.0004x over previous
.LBB0_394:
	s_lshl_b32 s4, s27, 3
	s_and_b32 s4, s4, 0x78
	s_ashr_i32 s28, s27, 8
	s_add_i32 s4, s4, s3
	s_ashr_i32 s29, s28, 31
	s_lshl_b32 s34, s4, 5
	s_lshl_b32 s35, s27, 10
	s_lshl_b64 s[28:29], s[28:29], 12
	s_and_b32 s35, s35, 0x3c000
	s_ashr_i32 s39, s34, 31
	s_add_u32 s38, s34, s35
	s_addc_u32 s39, s39, 0
	v_mov_b32_e32 v5, s39
	v_or_b32_e32 v4, s38, v126
	v_lshl_add_u64 v[4:5], v[4:5], 0, s[28:29]
	v_lshlrev_b64 v[4:5], 7, v[4:5]
	v_lshl_add_u64 v[6:7], v[128:129], 0, v[4:5]
	v_or_b32_e32 v8, 0x400, v4
	v_mov_b32_e32 v9, v5
	v_lshl_add_u64 v[8:9], v[128:129], 0, v[8:9]
	global_load_dwordx4 v[92:95], v[6:7], off
	global_load_dwordx4 v[88:91], v[8:9], off
	v_or_b32_e32 v6, 0x800, v4
	v_mov_b32_e32 v7, v5
	v_lshl_add_u64 v[6:7], v[128:129], 0, v[6:7]
	v_or_b32_e32 v4, 0xc00, v4
	v_lshl_add_u64 v[4:5], v[128:129], 0, v[4:5]
	global_load_dwordx4 v[84:87], v[6:7], off
	global_load_dwordx4 v[80:83], v[4:5], off
	s_cmp_gt_i32 s4, 0
	s_cselect_b64 vcc, -1, 0
	s_cmp_lt_i32 s4, 1
	s_waitcnt vmcnt(11)
	ds_write_b128 v161, v[64:67]
	s_waitcnt vmcnt(10)
	ds_write_b128 v161, v[68:71] offset:512
	s_waitcnt vmcnt(5)
	ds_write_b128 v161, v[72:75] offset:1024
	s_waitcnt vmcnt(4)
	ds_write_b128 v161, v[76:79] offset:1536
	s_cbranch_scc1 .LBB0_396
	global_load_dwordx4 v[108:111], v[138:139], off offset:-4096
	global_load_dwordx4 v[112:115], v[138:139], off offset:-4064
	global_load_dwordx4 v[64:67], v[136:137], off offset:-4096
	global_load_dwordx4 v[68:71], v[136:137], off offset:-3072
	global_load_dwordx4 v[116:119], v[138:139], off offset:-4032
	global_load_dwordx4 v[120:123], v[138:139], off offset:-4000
	global_load_dwordx4 v[72:75], v[136:137], off offset:-2048
	global_load_dwordx4 v[76:79], v[136:137], off offset:-1024
	v_lshl_add_u64 v[138:139], v[138:139], 0, s[0:1]
	v_lshl_add_u64 v[136:137], v[136:137], 0, s[0:1]
	s_branch .LBB0_397

.LBB0_399:
	s_waitcnt vmcnt(0)
	s_and_b64 vcc, exec, s[34:35]
	s_cbranch_vccnz .LBB0_405
.LBB0_400:
	v_cmp_ge_f32_e32 vcc, 0x8000, v146
	s_cmp_eq_u64 vcc, exec
	s_mov_b64 s[34:35], -1
	s_cbranch_scc1 .LBB0_399
	s_cmp_eq_u32 s80, 2
	s_cbranch_scc1 .LBB0_403
	s_waitcnt vmcnt(2)
	v_mfma_f32_32x32x16_bf16 v[32:47], v[108:111], v[48:51], 0
	v_mfma_f32_32x32x16_bf16 v[32:47], v[112:115], v[52:55], v[32:47]
	v_mfma_f32_32x32x16_bf16 v[32:47], v[116:119], v[56:59], v[32:47]
	v_mfma_f32_32x32x16_bf16 v[32:47], v[120:123], v[60:63], v[32:47]
	s_waitcnt vmcnt(5)
	ds_write_b128 v161, v[64:67]
	s_waitcnt vmcnt(4)
	ds_write_b128 v161, v[68:71] offset:512
	s_waitcnt vmcnt(1)
	ds_write_b128 v161, v[72:75] offset:1024
	s_waitcnt vmcnt(0)
	ds_write_b128 v161, v[76:79] offset:1536
	global_load_dwordx4 v[108:111], v[138:139], off offset:-4096
	global_load_dwordx4 v[112:115], v[138:139], off offset:-4064
	global_load_dwordx4 v[64:67], v[136:137], off offset:-4096
	global_load_dwordx4 v[68:71], v[136:137], off offset:-3072
	global_load_dwordx4 v[116:119], v[138:139], off offset:-4032
	global_load_dwordx4 v[120:123], v[138:139], off offset:-4000
	global_load_dwordx4 v[72:75], v[136:137], off offset:-2048
	global_load_dwordx4 v[76:79], v[136:137], off offset:-1024
	v_lshl_add_u64 v[138:139], v[138:139], 0, s[0:1]
	v_lshl_add_u64 v[136:137], v[136:137], 0, s[0:1]
	s_branch .LBB0_404
.LBB0_403:
	s_waitcnt vmcnt(2)
	v_mfma_f32_32x32x16_bf16 v[32:47], v[108:111], v[48:51], 0
	v_mfma_f32_32x32x16_bf16 v[32:47], v[112:115], v[52:55], v[32:47]
	v_mfma_f32_32x32x16_bf16 v[32:47], v[116:119], v[56:59], v[32:47]
	v_mfma_f32_32x32x16_bf16 v[32:47], v[120:123], v[60:63], v[32:47]
	s_waitcnt vmcnt(5)
	ds_write_b128 v161, v[64:67]
	s_waitcnt vmcnt(4)
	ds_write_b128 v161, v[68:71] offset:512
	s_waitcnt vmcnt(1)
	ds_write_b128 v161, v[72:75] offset:1024
	s_waitcnt vmcnt(0)
	ds_write_b128 v161, v[76:79] offset:1536
.LBB0_404:
	s_add_i32 s80, s80, -1
	s_cmp_lt_u32 s80, 2
	s_cselect_b64 s[34:35], -1, 0
	s_nop 1
	v_mul_f32_e32 v33, 0xbfb8aa3b, v33
	v_mul_f32_e32 v34, 0xbfb8aa3b, v34
	v_exp_f32_e32 v33, v33
	v_exp_f32_e32 v34, v34
	v_mul_f32_e32 v41, 0xbfb8aa3b, v41
	v_exp_f32_e32 v41, v41
	v_add_f32_e32 v33, 1.0, v33
	v_add_f32_e32 v96, 1.0, v34
	v_mul_f32_e32 v42, 0xbfb8aa3b, v42
	v_rcp_f32_e32 v34, v33
	v_rcp_f32_e32 v33, v96
	v_exp_f32_e32 v96, v42
	v_add_f32_e32 v41, 1.0, v41
	v_mul_f32_e32 v42, 0xbfb8aa3b, v43
	v_mul_f32_e32 v45, 0xbfb8aa3b, v45
	v_mul_f32_e32 v46, 0xbfb8aa3b, v46
	v_mul_f32_e32 v40, 0xbfb8aa3b, v40
	v_exp_f32_e32 v43, v42
	v_rcp_f32_e32 v42, v41
	v_add_f32_e32 v41, 1.0, v96
	v_mul_f32_e32 v44, 0xbfb8aa3b, v44
	v_exp_f32_e32 v45, v45
	v_exp_f32_e32 v96, v46
	v_mul_f32_e32 v46, 0xbfb8aa3b, v47
	v_exp_f32_e32 v40, v40
	v_exp_f32_e32 v44, v44
	v_exp_f32_e32 v47, v46
	v_add_f32_e32 v45, 1.0, v45
	v_add_f32_e32 v40, 1.0, v40
	v_add_f32_e32 v43, 1.0, v43
	v_add_f32_e32 v44, 1.0, v44
	v_rcp_f32_e32 v46, v45
	v_add_f32_e32 v45, 1.0, v96
	v_add_f32_e32 v47, 1.0, v47
	v_rcp_f32_e32 v40, v40
	v_rcp_f32_e32 v41, v41
	v_rcp_f32_e32 v43, v43
	v_rcp_f32_e32 v44, v44
	v_rcp_f32_e32 v45, v45
	v_rcp_f32_e32 v47, v47
	v_mul_f32_e32 v36, 0xbfb8aa3b, v36
	v_mul_f32_e32 v37, 0xbfb8aa3b, v37
	v_mul_f32_e32 v38, 0xbfb8aa3b, v38
	v_mul_f32_e32 v39, 0xbfb8aa3b, v39
	v_exp_f32_e32 v36, v36
	v_exp_f32_e32 v37, v37
	v_exp_f32_e32 v38, v38
	v_exp_f32_e32 v39, v39
	v_pk_add_f32 v[98:99], v[40:41], 1.0 op_sel_hi:[1,0] neg_lo:[1,0] neg_hi:[1,0]
	v_pk_add_f32 v[100:101], v[42:43], 1.0 op_sel_hi:[1,0] neg_lo:[1,0] neg_hi:[1,0]
	v_pk_add_f32 v[102:103], v[44:45], 1.0 op_sel_hi:[1,0] neg_lo:[1,0] neg_hi:[1,0]
	v_pk_add_f32 v[104:105], v[46:47], 1.0 op_sel_hi:[1,0] neg_lo:[1,0] neg_hi:[1,0]
	v_pk_mul_f32 v[98:99], v[98:99], v[100:101]
	v_pk_mul_f32 v[102:103], v[102:103], v[104:105]
	v_mov_b32_e32 v107, v98
	v_mov_b32_e32 v106, v102
	v_mov_b32_e32 v98, v103
	v_add_f32_e32 v36, 1.0, v36
	v_add_f32_e32 v37, 1.0, v37
	v_add_f32_e32 v97, 1.0, v38
	v_add_f32_e32 v39, 1.0, v39
	v_pk_mul_f32 v[106:107], v[106:107], v[98:99]
	v_mul_f32_e32 v32, 0xbfb8aa3b, v32
	v_mul_f32_e32 v35, 0xbfb8aa3b, v35
	v_rcp_f32_e32 v36, v36
	v_rcp_f32_e32 v38, v37
	v_rcp_f32_e32 v37, v97
	v_rcp_f32_e32 v39, v39
	ds_bpermute_b32 v167, v159, v107
	ds_bpermute_b32 v166, v159, v106
	v_exp_f32_e32 v32, v32
	v_exp_f32_e32 v35, v35
	v_pk_add_f32 v[170:171], v[36:37], 1.0 op_sel_hi:[1,0] neg_lo:[1,0] neg_hi:[1,0]
	v_pk_add_f32 v[172:173], v[38:39], 1.0 op_sel_hi:[1,0] neg_lo:[1,0] neg_hi:[1,0]
	v_add_f32_e32 v32, 1.0, v32
	v_add_f32_e32 v35, 1.0, v35
	v_pk_mul_f32 v[170:171], v[170:171], v[172:173]
	s_waitcnt lgkmcnt(0)
	v_pk_mul_f32 v[106:107], v[106:107], v[166:167]
	v_rcp_f32_e32 v32, v32
	v_rcp_f32_e32 v35, v35
	v_mov_b32_e32 v174, v170
	v_mov_b32_e32 v175, v106
	v_mov_b32_e32 v176, v171
	v_mov_b32_e32 v177, v107
	v_pk_mul_f32 v[174:175], v[174:175], v[176:177]
	ds_bpermute_b32 v177, v159, v174
	v_pk_add_f32 v[96:97], v[32:33], 1.0 op_sel_hi:[1,0] neg_lo:[1,0] neg_hi:[1,0]
	v_pk_add_f32 v[168:169], v[34:35], 1.0 op_sel_hi:[1,0] neg_lo:[1,0] neg_hi:[1,0]
	v_mov_b32_e32 v179, v174
	v_pk_mul_f32 v[96:97], v[96:97], v[168:169]
	v_mov_b32_e32 v182, v168
	v_mov_b32_e32 v178, v96
	v_mov_b32_e32 v176, v97
	s_waitcnt lgkmcnt(0)
	v_pk_mul_f32 v[178:179], v[178:179], v[176:177]
	ds_bpermute_b32 v174, v159, v178
	v_mov_b32_e32 v180, v97
	v_cndmask_b32_e64 v102, 1.0, v166, s[40:41]
	v_mov_b32_e32 v147, v104
	s_waitcnt lgkmcnt(0)
	v_pk_mul_f32 v[178:179], v[178:179], v[174:175]
	s_nop 0
	v_mul_f32_e32 v181, v146, v179
	v_cndmask_b32_e64 v183, 1.0, v174, s[40:41]
	v_pk_mul_f32 v[180:181], v[182:183], v[180:181]
	s_nop 0
	v_mul_f32_e32 v96, v180, v181
	v_mul_f32_e32 v96, v32, v96
	v_mul_f32_e32 v32, v97, v181
	v_mul_f32_e32 v97, v34, v32
	v_mul_f32_e32 v32, v169, v181
	v_mul_f32_e32 v98, v33, v32
	v_mul_f32_e32 v107, v35, v181
	v_mul_f32_e32 v33, v146, v175
	v_cndmask_b32_e64 v35, 1.0, v177, s[40:41]
	v_mov_b32_e32 v34, v172
	v_mov_b32_e32 v32, v171
	v_pk_mul_f32 v[32:33], v[34:35], v[32:33]
	v_cndmask_b32_e64 v35, 1.0, v167, s[40:41]
	v_mul_f32_e32 v32, v32, v33
	v_mul_f32_e32 v36, v36, v32
	v_mul_f32_e32 v32, v171, v33
	v_mul_f32_e32 v38, v38, v32
	v_mul_f32_e32 v32, v173, v33
	v_mul_f32_e32 v37, v37, v32
	v_mul_f32_e32 v39, v39, v33
	v_mul_f32_e32 v33, v146, v106
	v_mov_b32_e32 v34, v100
	v_mov_b32_e32 v32, v99
	v_pk_mul_f32 v[32:33], v[34:35], v[32:33]
	s_nop 0
	v_mul_f32_e32 v32, v32, v33
	v_mul_f32_e32 v40, v40, v32
	v_mul_f32_e32 v32, v99, v33
	v_mul_f32_e32 v42, v42, v32
	v_mul_f32_e32 v32, v101, v33
	v_mul_f32_e32 v41, v41, v32
	v_mul_f32_e32 v43, v43, v33
	v_pk_mul_f32 v[32:33], v[146:147], v[102:103]
	s_nop 0
	v_mul_f32_e32 v33, v32, v33
	v_mul_f32_e32 v44, v44, v33
	v_mul_f32_e32 v33, v32, v103
	v_mul_f32_e32 v46, v46, v33
	v_mul_f32_e32 v33, v32, v105
	v_mul_f32_e32 v45, v45, v33
	v_mul_f32_e32 v47, v47, v32
	v_cvt_pk_bf16_f32 v32, v96, v97
	v_cvt_pk_bf16_f32 v33, v98, v107
	v_cvt_pk_bf16_f32 v34, v36, v38
	v_cvt_pk_bf16_f32 v35, v37, v39
	v_cvt_pk_bf16_f32 v36, v40, v42
	v_cvt_pk_bf16_f32 v37, v41, v43
	v_cvt_pk_bf16_f32 v38, v44, v46
	v_cvt_pk_bf16_f32 v39, v45, v47
	ds_read_b64_tr_b16 v[40:41], v162
	ds_read_b64_tr_b16 v[42:43], v162 offset:512
	ds_read_b64_tr_b16 v[44:45], v162 offset:2048
	ds_read_b64_tr_b16 v[46:47], v162 offset:2560
	ds_read_b64_tr_b16 v[96:97], v162 offset:1024
	ds_read_b64_tr_b16 v[98:99], v162 offset:1536
	ds_read_b64_tr_b16 v[100:101], v162 offset:3072
	ds_read_b64_tr_b16 v[102:103], v162 offset:3584
	s_waitcnt lgkmcnt(6)
	v_mfma_f32_32x32x16_bf16 v[0:15], v[32:35], v[40:43], v[0:15]
	s_waitcnt lgkmcnt(4)
	v_mfma_f32_32x32x16_bf16 v[16:31], v[32:35], v[44:47], v[16:31]
	s_waitcnt lgkmcnt(2)
	v_mfma_f32_32x32x16_bf16 v[0:15], v[36:39], v[96:99], v[0:15]
	s_waitcnt lgkmcnt(0)
	v_mfma_f32_32x32x16_bf16 v[16:31], v[36:39], v[100:103], v[16:31]
	v_mul_f32_e32 v32, v178, v179
	v_mul_f32_e32 v146, v146, v32
	s_and_b64 vcc, exec, s[34:35]
	s_cbranch_vccz .LBB0_400
